# spatial phase: LDS fragment reads software-pipelined one K-group ahead into fresh VGPRs (counted lgkmcnt instead of per-MFMA lgkmcnt(0))
# speedup vs baseline: 1.0130x; 1.0130x over previous
.LBB0_912:
	ds_read_b128 v[50:53], v160
	ds_read_b128 v[54:57], v165
	ds_read_b128 v[58:61], v165 offset:4352
	ds_read_b128 v[62:65], v165 offset:8704
	ds_read_b128 v[140:143], v165 offset:13056
	ds_read_b128 v[144:147], v165 offset:17408
	ds_read_b128 v[148:151], v165 offset:21760
	ds_read_b128 v[152:155], v165 offset:26112
	ds_read_b128 v[170:173], v165 offset:30464
	ds_read_b128 v[200:203], v160 offset:64
	s_waitcnt lgkmcnt(8)
	v_mfma_f32_16x16x32_bf16 v[54:57], v[50:53], v[54:57], 0
	ds_read_b128 v[204:207], v165 offset:64
	s_waitcnt vmcnt(27)
	v_permlane16_swap_b32_e32 v78, v80
	v_lshlrev_b32_e32 v169, 16, v78
	s_waitcnt lgkmcnt(8)
	v_mfma_f32_16x16x32_bf16 v[58:61], v[50:53], v[58:61], 0
	ds_read_b128 v[208:211], v165 offset:4416
	v_and_b32_e32 v78, 0xffff0000, v78
	v_permlane16_swap_b32_e32 v79, v81
	s_waitcnt lgkmcnt(8)
	v_mfma_f32_16x16x32_bf16 v[62:65], v[50:53], v[62:65], 0
	ds_read_b128 v[212:215], v165 offset:8768
	s_andn2_b64 vcc, exec, s[12:13]
	s_mov_b32 s15, s14
	s_waitcnt lgkmcnt(8)
	v_mfma_f32_16x16x32_bf16 v[140:143], v[50:53], v[140:143], 0
	ds_read_b128 v[216:219], v165 offset:13120
	s_waitcnt lgkmcnt(8)
	v_mfma_f32_16x16x32_bf16 v[144:147], v[50:53], v[144:147], 0
	ds_read_b128 v[220:223], v165 offset:17472
	s_waitcnt lgkmcnt(8)
	v_mfma_f32_16x16x32_bf16 v[148:151], v[50:53], v[148:151], 0
	ds_read_b128 v[224:227], v165 offset:21824
	s_waitcnt lgkmcnt(8)
	v_mfma_f32_16x16x32_bf16 v[152:155], v[50:53], v[152:155], 0
	ds_read_b128 v[228:231], v165 offset:26176
	s_waitcnt lgkmcnt(8)
	v_mfma_f32_16x16x32_bf16 v[50:53], v[50:53], v[170:173], 0
	ds_read_b128 v[232:235], v165 offset:30528
	ds_read_b128 v[244:247], v160 offset:128
	s_waitcnt lgkmcnt(8)
	v_mfma_f32_16x16x32_bf16 v[54:57], v[200:203], v[204:207], v[54:57]
	ds_read_b128 v[204:207], v165 offset:128
	s_waitcnt lgkmcnt(8)
	v_mfma_f32_16x16x32_bf16 v[58:61], v[200:203], v[208:211], v[58:61]
	ds_read_b128 v[208:211], v165 offset:4480
	s_waitcnt lgkmcnt(8)
	v_mfma_f32_16x16x32_bf16 v[62:65], v[200:203], v[212:215], v[62:65]
	ds_read_b128 v[212:215], v165 offset:8832
	s_waitcnt lgkmcnt(8)
	v_mfma_f32_16x16x32_bf16 v[140:143], v[200:203], v[216:219], v[140:143]
	ds_read_b128 v[216:219], v165 offset:13184
	s_waitcnt lgkmcnt(8)
	v_mfma_f32_16x16x32_bf16 v[144:147], v[200:203], v[220:223], v[144:147]
	ds_read_b128 v[220:223], v165 offset:17536
	s_waitcnt lgkmcnt(8)
	v_mfma_f32_16x16x32_bf16 v[148:151], v[200:203], v[224:227], v[148:151]
	ds_read_b128 v[224:227], v165 offset:21888
	s_waitcnt lgkmcnt(8)
	v_mfma_f32_16x16x32_bf16 v[152:155], v[200:203], v[228:231], v[152:155]
	ds_read_b128 v[228:231], v165 offset:26240
	s_waitcnt lgkmcnt(8)
	v_mfma_f32_16x16x32_bf16 v[50:53], v[200:203], v[232:235], v[50:53]
	ds_read_b128 v[232:235], v165 offset:30592
	ds_read_b128 v[200:203], v160 offset:192
	s_waitcnt lgkmcnt(8)
	v_mfma_f32_16x16x32_bf16 v[54:57], v[244:247], v[204:207], v[54:57]
	ds_read_b128 v[204:207], v165 offset:192
	s_waitcnt lgkmcnt(8)
	v_mfma_f32_16x16x32_bf16 v[58:61], v[244:247], v[208:211], v[58:61]
	ds_read_b128 v[208:211], v165 offset:4544
	s_waitcnt lgkmcnt(8)
	v_mfma_f32_16x16x32_bf16 v[62:65], v[244:247], v[212:215], v[62:65]
	ds_read_b128 v[212:215], v165 offset:8896
	s_waitcnt lgkmcnt(8)
	v_mfma_f32_16x16x32_bf16 v[140:143], v[244:247], v[216:219], v[140:143]
	ds_read_b128 v[216:219], v165 offset:13248
	s_waitcnt lgkmcnt(8)
	v_mfma_f32_16x16x32_bf16 v[144:147], v[244:247], v[220:223], v[144:147]
	ds_read_b128 v[220:223], v165 offset:17600
	s_waitcnt lgkmcnt(8)
	v_mfma_f32_16x16x32_bf16 v[148:151], v[244:247], v[224:227], v[148:151]
	ds_read_b128 v[224:227], v165 offset:21952
	s_waitcnt lgkmcnt(8)
	v_mfma_f32_16x16x32_bf16 v[152:155], v[244:247], v[228:231], v[152:155]
	ds_read_b128 v[228:231], v165 offset:26304
	s_waitcnt lgkmcnt(8)
	v_mfma_f32_16x16x32_bf16 v[50:53], v[244:247], v[232:235], v[50:53]
	ds_read_b128 v[232:235], v165 offset:30656
	s_waitcnt lgkmcnt(7)
	v_mfma_f32_16x16x32_bf16 v[54:57], v[200:203], v[204:207], v[54:57]
	s_waitcnt lgkmcnt(6)
	v_mfma_f32_16x16x32_bf16 v[58:61], v[200:203], v[208:211], v[58:61]
	s_waitcnt lgkmcnt(5)
	v_mfma_f32_16x16x32_bf16 v[62:65], v[200:203], v[212:215], v[62:65]
	s_waitcnt lgkmcnt(4)
	v_mfma_f32_16x16x32_bf16 v[140:143], v[200:203], v[216:219], v[140:143]
	s_waitcnt lgkmcnt(3)
	v_mfma_f32_16x16x32_bf16 v[144:147], v[200:203], v[220:223], v[144:147]
	s_waitcnt lgkmcnt(2)
	v_mfma_f32_16x16x32_bf16 v[148:151], v[200:203], v[224:227], v[148:151]
	s_waitcnt lgkmcnt(1)
	v_mfma_f32_16x16x32_bf16 v[152:155], v[200:203], v[228:231], v[152:155]
	s_waitcnt lgkmcnt(0)
	v_mfma_f32_16x16x32_bf16 v[50:53], v[200:203], v[232:235], v[50:53]
	ds_read2_b32 v[170:171], v161 offset1:16
	s_waitcnt lgkmcnt(0)
	v_add_f32_e32 v54, v54, v170
	v_add_f32_e32 v55, v55, v170
	v_mul_f32_e32 v54, v54, v169
	v_mul_f32_e32 v55, v55, v78
	v_cvt_pk_bf16_f32 v54, v54, v55
	v_add_f32_e32 v55, v56, v170
	v_lshlrev_b32_e32 v56, 16, v79
	v_mul_f32_e32 v55, v55, v56
	v_add_f32_e32 v56, v57, v170
	v_and_b32_e32 v57, 0xffff0000, v79
	v_mul_f32_e32 v56, v56, v57
	v_cvt_pk_bf16_f32 v55, v55, v56
	v_add_f32_e32 v56, v58, v171
	v_lshlrev_b32_e32 v57, 16, v80
	v_mul_f32_e32 v56, v56, v57
	v_add_f32_e32 v57, v59, v171
	v_and_b32_e32 v58, 0xffff0000, v80
	v_mul_f32_e32 v57, v57, v58
	v_cvt_pk_bf16_f32 v56, v56, v57
	v_add_f32_e32 v57, v60, v171
	v_lshlrev_b32_e32 v58, 16, v81
	v_mul_f32_e32 v57, v57, v58
	v_add_f32_e32 v58, v61, v171
	v_and_b32_e32 v59, 0xffff0000, v81
	v_mul_f32_e32 v58, v58, v59
	v_cvt_pk_bf16_f32 v57, v57, v58
	v_permlane16_swap_b32_e32 v54, v56
	v_permlane16_swap_b32_e32 v55, v57
	global_store_dwordx4 v[88:89], v[54:57], off offset:512
	ds_read2_b32 v[56:57], v161 offset0:32 offset1:48
	s_waitcnt vmcnt(27)
	v_mov_b32_e32 v58, v76
	s_nop 1
	v_permlane16_swap_b32_e32 v74, v58
	v_lshlrev_b32_e32 v55, 16, v74
	s_waitcnt lgkmcnt(0)
	v_add_f32_e32 v54, v62, v56
	v_mov_b32_e32 v59, v77
	v_mul_f32_e32 v54, v54, v55
	v_add_f32_e32 v55, v63, v56
	v_and_b32_e32 v60, 0xffff0000, v74
	v_permlane16_swap_b32_e32 v75, v59
	v_mul_f32_e32 v55, v55, v60
	v_cvt_pk_bf16_f32 v54, v54, v55
	v_add_f32_e32 v55, v64, v56
	v_lshlrev_b32_e32 v60, 16, v75
	v_mul_f32_e32 v55, v55, v60
	v_add_f32_e32 v56, v65, v56
	v_and_b32_e32 v60, 0xffff0000, v75
	v_mul_f32_e32 v56, v56, v60
	v_cvt_pk_bf16_f32 v55, v55, v56
	v_add_f32_e32 v56, v140, v57
	v_lshlrev_b32_e32 v60, 16, v58
	v_mul_f32_e32 v56, v56, v60
	v_add_f32_e32 v60, v141, v57
	v_and_b32_e32 v58, 0xffff0000, v58
	v_mul_f32_e32 v58, v60, v58
	v_cvt_pk_bf16_f32 v56, v56, v58
	v_add_f32_e32 v58, v142, v57
	v_lshlrev_b32_e32 v60, 16, v59
	v_add_f32_e32 v57, v143, v57
	v_and_b32_e32 v59, 0xffff0000, v59
	v_mul_f32_e32 v57, v57, v59
	v_mul_f32_e32 v58, v58, v60
	v_cvt_pk_bf16_f32 v57, v58, v57
	v_permlane16_swap_b32_e32 v54, v56
	v_permlane16_swap_b32_e32 v55, v57
	global_store_dwordx4 v[86:87], v[54:57], off offset:512
	ds_read2_b32 v[56:57], v161 offset0:64 offset1:80
	s_waitcnt vmcnt(27)
	v_mov_b32_e32 v58, v72
	s_nop 1
	v_permlane16_swap_b32_e32 v70, v58
	v_lshlrev_b32_e32 v55, 16, v70
	s_waitcnt lgkmcnt(0)
	v_add_f32_e32 v54, v144, v56
	v_mov_b32_e32 v59, v73
	v_mul_f32_e32 v54, v54, v55
	v_add_f32_e32 v55, v145, v56
	v_and_b32_e32 v60, 0xffff0000, v70
	v_permlane16_swap_b32_e32 v71, v59
	v_mul_f32_e32 v55, v55, v60
	v_cvt_pk_bf16_f32 v54, v54, v55
	v_add_f32_e32 v55, v146, v56
	v_lshlrev_b32_e32 v60, 16, v71
	v_mul_f32_e32 v55, v55, v60
	v_add_f32_e32 v56, v147, v56
	v_and_b32_e32 v60, 0xffff0000, v71
	v_mul_f32_e32 v56, v56, v60
	v_cvt_pk_bf16_f32 v55, v55, v56
	v_add_f32_e32 v56, v148, v57
	v_lshlrev_b32_e32 v60, 16, v58
	v_mul_f32_e32 v56, v56, v60
	v_add_f32_e32 v60, v149, v57
	v_and_b32_e32 v58, 0xffff0000, v58
	v_mul_f32_e32 v58, v60, v58
	v_cvt_pk_bf16_f32 v56, v56, v58
	v_add_f32_e32 v58, v150, v57
	v_lshlrev_b32_e32 v60, 16, v59
	v_add_f32_e32 v57, v151, v57
	v_and_b32_e32 v59, 0xffff0000, v59
	v_mul_f32_e32 v57, v57, v59
	v_mul_f32_e32 v58, v58, v60
	v_cvt_pk_bf16_f32 v57, v58, v57
	v_permlane16_swap_b32_e32 v54, v56
	v_permlane16_swap_b32_e32 v55, v57
	global_store_dwordx4 v[82:83], v[54:57], off offset:512
	ds_read2_b32 v[56:57], v161 offset0:96 offset1:112
	s_waitcnt vmcnt(27)
	v_mov_b32_e32 v58, v68
	s_nop 1
	v_permlane16_swap_b32_e32 v66, v58
	v_lshlrev_b32_e32 v55, 16, v66
	s_waitcnt lgkmcnt(0)
	v_add_f32_e32 v54, v152, v56
	v_mov_b32_e32 v59, v69
	v_mul_f32_e32 v54, v54, v55
	v_add_f32_e32 v55, v153, v56
	v_and_b32_e32 v60, 0xffff0000, v66
	v_permlane16_swap_b32_e32 v67, v59
	v_mul_f32_e32 v55, v55, v60
	v_cvt_pk_bf16_f32 v54, v54, v55
	v_add_f32_e32 v55, v154, v56
	v_lshlrev_b32_e32 v60, 16, v67
	v_mul_f32_e32 v55, v55, v60
	v_add_f32_e32 v56, v155, v56
	v_and_b32_e32 v60, 0xffff0000, v67
	v_mul_f32_e32 v56, v56, v60
	v_cvt_pk_bf16_f32 v55, v55, v56
	v_add_f32_e32 v50, v50, v57
	v_lshlrev_b32_e32 v56, 16, v58
	v_mul_f32_e32 v50, v50, v56
	v_add_f32_e32 v51, v51, v57
	v_and_b32_e32 v56, 0xffff0000, v58
	v_mul_f32_e32 v51, v51, v56
	v_cvt_pk_bf16_f32 v56, v50, v51
	v_add_f32_e32 v50, v52, v57
	v_lshlrev_b32_e32 v51, 16, v59
	v_mul_f32_e32 v50, v50, v51
	v_add_f32_e32 v51, v53, v57
	v_and_b32_e32 v52, 0xffff0000, v59
	v_mul_f32_e32 v51, v51, v52
	v_cvt_pk_bf16_f32 v57, v50, v51
	v_permlane16_swap_b32_e32 v54, v56
	v_permlane16_swap_b32_e32 v55, v57
	global_store_dwordx4 v[84:85], v[54:57], off offset:512
	s_cbranch_vccz .LBB0_925

.LBB0_919:
	s_or_b64 exec, exec, s[12:13]
	s_waitcnt lgkmcnt(0)
	s_barrier
	s_waitcnt vmcnt(19)
	ds_write_b128 v166, v[2:5]
	s_waitcnt vmcnt(18)
	ds_write_b128 v166, v[6:9] offset:8704
	s_waitcnt vmcnt(17)
	ds_write_b128 v166, v[10:13] offset:17408
	s_waitcnt vmcnt(16)
	ds_write_b128 v166, v[14:17] offset:26112
	ds_read_b128 v[50:53], v167
	ds_read_b128 v[54:57], v167 offset:16
	ds_read_b128 v[58:61], v167 offset:32
	ds_read_b128 v[62:65], v167 offset:48
	s_waitcnt vmcnt(15)
	v_lshlrev_b32_e32 v66, 16, v46
	s_waitcnt lgkmcnt(3)
	v_sub_f32_e32 v50, v66, v50
	v_and_b32_e32 v46, 0xffff0000, v46
	v_mul_f32_e32 v50, v51, v50
	v_sub_f32_e32 v46, v46, v52
	v_lshlrev_b32_e32 v51, 16, v47
	v_and_b32_e32 v47, 0xffff0000, v47
	v_lshlrev_b32_e32 v52, 16, v48
	v_and_b32_e32 v48, 0xffff0000, v48
	v_mul_f32_e32 v46, v53, v46
	s_waitcnt lgkmcnt(2)
	v_sub_f32_e32 v47, v47, v56
	s_waitcnt lgkmcnt(1)
	v_sub_f32_e32 v48, v48, v60
	v_lshlrev_b32_e32 v53, 16, v49
	v_and_b32_e32 v49, 0xffff0000, v49
	v_sub_f32_e32 v51, v51, v54
	v_mul_f32_e32 v47, v57, v47
	v_sub_f32_e32 v52, v52, v58
	v_mul_f32_e32 v48, v61, v48
	s_waitcnt lgkmcnt(0)
	v_sub_f32_e32 v53, v53, v62
	v_sub_f32_e32 v49, v49, v64
	s_waitcnt vmcnt(7)
	v_fma_f32 v46, v96, v46, v97
	v_mul_f32_e32 v51, v55, v51
	v_fma_f32 v47, v96, v47, v97
	v_mul_f32_e32 v52, v59, v52
	v_fma_f32 v48, v96, v48, v97
	v_mul_f32_e32 v53, v63, v53
	v_mul_f32_e32 v49, v65, v49
	v_fma_f32 v50, v96, v50, v97
	v_fma_f32 v51, v96, v51, v97
	v_fma_f32 v52, v96, v52, v97
	v_fma_f32 v53, v96, v53, v97
	v_fmac_f32_e32 v97, v96, v49
	v_cvt_pk_bf16_f32 v46, v50, v46
	v_cvt_pk_bf16_f32 v47, v51, v47
	v_cvt_pk_bf16_f32 v48, v52, v48
	v_cvt_pk_bf16_f32 v49, v53, v97
	ds_write_b128 v168, v[46:49]
	ds_read_b128 v[46:49], v167
	ds_read_b128 v[50:53], v167 offset:16
	ds_read_b128 v[54:57], v167 offset:32
	ds_read_b128 v[58:61], v167 offset:48
	v_lshlrev_b32_e32 v62, 16, v38
	s_waitcnt lgkmcnt(3)
	v_sub_f32_e32 v46, v62, v46
	v_and_b32_e32 v38, 0xffff0000, v38
	v_mul_f32_e32 v46, v47, v46
	v_sub_f32_e32 v38, v38, v48
	v_lshlrev_b32_e32 v47, 16, v39
	v_and_b32_e32 v39, 0xffff0000, v39
	v_lshlrev_b32_e32 v48, 16, v40
	v_and_b32_e32 v40, 0xffff0000, v40
	v_mul_f32_e32 v38, v49, v38
	s_waitcnt lgkmcnt(2)
	v_sub_f32_e32 v39, v39, v52
	s_waitcnt lgkmcnt(1)
	v_sub_f32_e32 v40, v40, v56
	v_lshlrev_b32_e32 v49, 16, v41
	v_and_b32_e32 v41, 0xffff0000, v41
	v_sub_f32_e32 v47, v47, v50
	v_mul_f32_e32 v39, v53, v39
	v_sub_f32_e32 v48, v48, v54
	v_mul_f32_e32 v40, v57, v40
	s_waitcnt lgkmcnt(0)
	v_sub_f32_e32 v49, v49, v58
	v_sub_f32_e32 v41, v41, v60
	s_waitcnt vmcnt(6)
	v_fma_f32 v38, v94, v38, v95
	v_mul_f32_e32 v47, v51, v47
	v_fma_f32 v39, v94, v39, v95
	v_mul_f32_e32 v48, v55, v48
	v_fma_f32 v40, v94, v40, v95
	v_mul_f32_e32 v49, v59, v49
	v_mul_f32_e32 v41, v61, v41
	v_fma_f32 v46, v94, v46, v95
	v_fma_f32 v47, v94, v47, v95
	v_fma_f32 v48, v94, v48, v95
	v_fma_f32 v49, v94, v49, v95
	v_fmac_f32_e32 v95, v94, v41
	v_cvt_pk_bf16_f32 v38, v46, v38
	v_cvt_pk_bf16_f32 v39, v47, v39
	v_cvt_pk_bf16_f32 v40, v48, v40
	v_cvt_pk_bf16_f32 v41, v49, v95
	ds_write_b128 v168, v[38:41] offset:8704
	ds_read_b128 v[38:41], v167
	ds_read_b128 v[46:49], v167 offset:16
	ds_read_b128 v[50:53], v167 offset:32
	ds_read_b128 v[54:57], v167 offset:48
	v_lshlrev_b32_e32 v58, 16, v34
	s_waitcnt lgkmcnt(3)
	v_sub_f32_e32 v38, v58, v38
	v_and_b32_e32 v34, 0xffff0000, v34
	v_mul_f32_e32 v38, v39, v38
	v_sub_f32_e32 v34, v34, v40
	v_lshlrev_b32_e32 v39, 16, v35
	v_and_b32_e32 v35, 0xffff0000, v35
	v_lshlrev_b32_e32 v40, 16, v36
	v_and_b32_e32 v36, 0xffff0000, v36
	v_mul_f32_e32 v34, v41, v34
	s_waitcnt lgkmcnt(2)
	v_sub_f32_e32 v35, v35, v48
	s_waitcnt lgkmcnt(1)
	v_sub_f32_e32 v36, v36, v52
	v_lshlrev_b32_e32 v41, 16, v37
	v_and_b32_e32 v37, 0xffff0000, v37
	v_sub_f32_e32 v39, v39, v46
	v_mul_f32_e32 v35, v49, v35
	v_sub_f32_e32 v40, v40, v50
	v_mul_f32_e32 v36, v53, v36
	s_waitcnt lgkmcnt(0)
	v_sub_f32_e32 v41, v41, v54
	v_sub_f32_e32 v37, v37, v56
	s_waitcnt vmcnt(5)
	v_fma_f32 v34, v92, v34, v93
	v_mul_f32_e32 v39, v47, v39
	v_fma_f32 v35, v92, v35, v93
	v_mul_f32_e32 v40, v51, v40
	v_fma_f32 v36, v92, v36, v93
	v_mul_f32_e32 v41, v55, v41
	v_mul_f32_e32 v37, v57, v37
	v_fma_f32 v38, v92, v38, v93
	v_fma_f32 v39, v92, v39, v93
	v_fma_f32 v40, v92, v40, v93
	v_fma_f32 v41, v92, v41, v93
	v_fmac_f32_e32 v93, v92, v37
	v_cvt_pk_bf16_f32 v34, v38, v34
	v_cvt_pk_bf16_f32 v35, v39, v35
	v_cvt_pk_bf16_f32 v36, v40, v36
	v_cvt_pk_bf16_f32 v37, v41, v93
	ds_write_b128 v168, v[34:37] offset:17408
	ds_read_b128 v[34:37], v167
	ds_read_b128 v[38:41], v167 offset:16
	ds_read_b128 v[46:49], v167 offset:32
	ds_read_b128 v[50:53], v167 offset:48
	s_lshl_b32 s12, s15, 4
	v_lshlrev_b32_e32 v54, 16, v26
	s_and_b32 s16, s12, 0xffffff80
	s_waitcnt lgkmcnt(3)
	v_sub_f32_e32 v34, v54, v34
	v_and_b32_e32 v26, 0xffff0000, v26
	s_cmp_eq_u32 s17, 7
	v_mul_f32_e32 v34, v35, v34
	v_sub_f32_e32 v26, v26, v36
	v_lshlrev_b32_e32 v35, 16, v27
	v_and_b32_e32 v27, 0xffff0000, v27
	v_lshlrev_b32_e32 v36, 16, v28
	v_and_b32_e32 v28, 0xffff0000, v28
	s_cselect_b32 s14, s26, 1
	v_mul_f32_e32 v26, v37, v26
	s_waitcnt lgkmcnt(2)
	v_sub_f32_e32 v27, v27, v40
	s_waitcnt lgkmcnt(1)
	v_sub_f32_e32 v28, v28, v48
	v_lshlrev_b32_e32 v37, 16, v29
	v_and_b32_e32 v29, 0xffff0000, v29
	s_add_i32 s14, s14, s15
	v_sub_f32_e32 v35, v35, v38
	v_mul_f32_e32 v27, v41, v27
	v_sub_f32_e32 v36, v36, v46
	v_mul_f32_e32 v28, v49, v28
	s_waitcnt lgkmcnt(0)
	v_sub_f32_e32 v37, v37, v50
	v_sub_f32_e32 v29, v29, v52
	s_cmpk_gt_i32 s14, 0x7ff
	s_waitcnt vmcnt(4)
	v_fma_f32 v26, v90, v26, v91
	v_mul_f32_e32 v35, v39, v35
	v_fma_f32 v27, v90, v27, v91
	v_mul_f32_e32 v36, v47, v36
	v_fma_f32 v28, v90, v28, v91
	v_mul_f32_e32 v37, v51, v37
	v_mul_f32_e32 v29, v53, v29
	s_mul_i32 s18, s17, 0x180
	s_cselect_b64 s[12:13], -1, 0
	v_fma_f32 v34, v90, v34, v91
	v_fma_f32 v35, v90, v35, v91
	v_fma_f32 v36, v90, v36, v91
	v_fma_f32 v37, v90, v37, v91
	v_fmac_f32_e32 v91, v90, v29
	v_cvt_pk_bf16_f32 v26, v34, v26
	v_cvt_pk_bf16_f32 v27, v35, v27
	v_cvt_pk_bf16_f32 v28, v36, v28
	v_cvt_pk_bf16_f32 v29, v37, v91
	s_and_b32 s15, s15, 0xffffff8
	s_lshl_b32 s42, s18, 1
	s_ashr_i32 s17, s16, 31
	ds_write_b128 v168, v[26:29] offset:26112
	v_lshl_add_u64 v[28:29], s[16:17], 1, v[136:137]
	v_or_b32_e32 v66, s16, v164
	s_add_u32 s16, s60, s42
	s_addc_u32 s17, s61, 0
	v_mov_b64_e32 v[50:51], s[16:17]
	v_mad_i64_i32 v[52:53], s[16:17], v66, s85, v[50:51]
	v_lshl_add_u64 v[52:53], v[52:53], 0, v[138:139]
	v_add_u32_e32 v26, s18, v163
	v_lshl_add_u64 v[146:147], v[52:53], 0, v[0:1]
	v_or_b32_e32 v52, 32, v66
	v_ashrrev_i32_e32 v27, 31, v26
	v_mad_i64_i32 v[52:53], s[16:17], v52, s85, v[50:51]
	v_lshlrev_b64 v[26:27], 16, v[26:27]
	v_lshl_add_u64 v[52:53], v[52:53], 0, v[138:139]
	v_or_b32_e32 v177, s15, v162
	v_lshl_add_u64 v[140:141], v[28:29], 0, v[26:27]
	s_mov_b32 s15, 0x200000
	v_lshl_add_u64 v[148:149], v[52:53], 0, v[0:1]
	v_or_b32_e32 v52, 64, v66
	v_lshl_add_u64 v[154:155], v[134:135], 0, s[42:43]
	s_lshl_b32 s42, s18, 2
	v_add_co_u32_e32 v26, vcc, s15, v140
	v_mad_i64_i32 v[52:53], s[16:17], v52, s85, v[50:51]
	v_lshl_add_u64 v[142:143], v[130:131], 0, s[42:43]
	v_lshl_add_u64 v[144:145], v[132:133], 0, s[42:43]
	v_addc_co_u32_e32 v27, vcc, 0, v141, vcc
	s_mov_b32 s15, 0x400000
	v_lshl_add_u64 v[52:53], v[52:53], 0, v[138:139]
	s_waitcnt lgkmcnt(0)
	s_barrier
	global_load_dwordx4 v[46:49], v[140:141], off
	global_load_dword v176, v[142:143], off offset:512
	global_load_dword v175, v[144:145], off offset:512
	global_load_dwordx4 v[38:41], v[26:27], off
	global_load_dword v174, v[142:143], off offset:640
	global_load_dword v173, v[144:145], off offset:640
	v_add_co_u32_e32 v26, vcc, s15, v140
	v_lshl_add_u64 v[150:151], v[52:53], 0, v[0:1]
	v_or_b32_e32 v52, 0x60, v66
	v_addc_co_u32_e32 v27, vcc, 0, v141, vcc
	v_mad_i64_i32 v[50:51], s[16:17], v52, s85, v[50:51]
	global_load_dwordx4 v[34:37], v[26:27], off
	global_load_dword v172, v[142:143], off offset:768
	global_load_dword v171, v[144:145], off offset:768
	v_add_co_u32_e32 v26, vcc, s27, v140
	v_lshl_add_u64 v[50:51], v[50:51], 0, v[138:139]
	s_nop 0
	v_addc_co_u32_e32 v27, vcc, 0, v141, vcc
	v_lshl_add_u64 v[152:153], v[50:51], 0, v[0:1]
	global_load_dwordx4 v[26:29], v[26:27], off
	s_nop 0
	global_load_dword v170, v[142:143], off offset:896
	global_load_dword v169, v[144:145], off offset:896
	global_load_dwordx4 v[62:65], v[146:147], off offset:256
	global_load_dwordx4 v[58:61], v[148:149], off offset:256
	global_load_dwordx4 v[54:57], v[150:151], off offset:256
	global_load_dwordx4 v[50:53], v[152:153], off offset:256
	ds_read_b128 v[66:69], v160
	ds_read_b128 v[70:73], v165
	ds_read_b128 v[74:77], v165 offset:4352
	ds_read_b128 v[78:81], v165 offset:8704
	ds_read_b128 v[82:85], v165 offset:13056
	ds_read_b128 v[86:89], v165 offset:17408
	ds_read_b128 v[90:93], v165 offset:21760
	ds_read_b128 v[94:97], v165 offset:26112
	ds_read_b128 v[178:181], v165 offset:30464
	ds_read_b128 v[200:203], v160 offset:64
	s_waitcnt lgkmcnt(8)
	v_mfma_f32_16x16x32_bf16 v[70:73], v[66:69], v[70:73], 0
	ds_read_b128 v[204:207], v165 offset:64
	s_waitcnt vmcnt(19)
	v_permlane16_swap_b32_e32 v42, v44
	v_permlane16_swap_b32_e32 v43, v45
	s_waitcnt lgkmcnt(8)
	v_mfma_f32_16x16x32_bf16 v[74:77], v[66:69], v[74:77], 0
	ds_read_b128 v[208:211], v165 offset:4416
	s_waitcnt vmcnt(18)
	v_permlane16_swap_b32_e32 v30, v32
	v_permlane16_swap_b32_e32 v31, v33
	s_waitcnt lgkmcnt(8)
	v_mfma_f32_16x16x32_bf16 v[78:81], v[66:69], v[78:81], 0
	ds_read_b128 v[212:215], v165 offset:8768
	s_waitcnt vmcnt(17)
	v_permlane16_swap_b32_e32 v22, v24
	v_permlane16_swap_b32_e32 v23, v25
	s_waitcnt lgkmcnt(8)
	v_mfma_f32_16x16x32_bf16 v[82:85], v[66:69], v[82:85], 0
	ds_read_b128 v[216:219], v165 offset:13120
	s_waitcnt vmcnt(16)
	v_permlane16_swap_b32_e32 v18, v20
	v_permlane16_swap_b32_e32 v19, v21
	s_waitcnt lgkmcnt(8)
	v_mfma_f32_16x16x32_bf16 v[86:89], v[66:69], v[86:89], 0
	ds_read_b128 v[220:223], v165 offset:17472
	s_mov_b32 s15, 0x800000
	s_waitcnt vmcnt(3)
	v_permlane16_swap_b32_e32 v62, v64
	s_waitcnt lgkmcnt(8)
	v_mfma_f32_16x16x32_bf16 v[90:93], v[66:69], v[90:93], 0
	ds_read_b128 v[224:227], v165 offset:21824
	v_permlane16_swap_b32_e32 v63, v65
	s_waitcnt vmcnt(2)
	v_permlane16_swap_b32_e32 v58, v60
	s_waitcnt lgkmcnt(8)
	v_mfma_f32_16x16x32_bf16 v[94:97], v[66:69], v[94:97], 0
	ds_read_b128 v[228:231], v165 offset:26176
	v_permlane16_swap_b32_e32 v59, v61
	s_waitcnt vmcnt(1)
	v_permlane16_swap_b32_e32 v54, v56
	s_waitcnt lgkmcnt(8)
	v_mfma_f32_16x16x32_bf16 v[66:69], v[66:69], v[178:181], 0
	ds_read_b128 v[232:235], v165 offset:30528
	v_permlane16_swap_b32_e32 v55, v57
	ds_read_b128 v[244:247], v160 offset:128
	s_waitcnt lgkmcnt(8)
	v_mfma_f32_16x16x32_bf16 v[70:73], v[200:203], v[204:207], v[70:73]
	ds_read_b128 v[204:207], v165 offset:128
	s_waitcnt lgkmcnt(8)
	v_mfma_f32_16x16x32_bf16 v[74:77], v[200:203], v[208:211], v[74:77]
	ds_read_b128 v[208:211], v165 offset:4480
	s_waitcnt lgkmcnt(8)
	v_mfma_f32_16x16x32_bf16 v[78:81], v[200:203], v[212:215], v[78:81]
	ds_read_b128 v[212:215], v165 offset:8832
	s_waitcnt lgkmcnt(8)
	v_mfma_f32_16x16x32_bf16 v[82:85], v[200:203], v[216:219], v[82:85]
	ds_read_b128 v[216:219], v165 offset:13184
	s_waitcnt lgkmcnt(8)
	v_mfma_f32_16x16x32_bf16 v[86:89], v[200:203], v[220:223], v[86:89]
	ds_read_b128 v[220:223], v165 offset:17536
	s_waitcnt lgkmcnt(8)
	v_mfma_f32_16x16x32_bf16 v[90:93], v[200:203], v[224:227], v[90:93]
	ds_read_b128 v[224:227], v165 offset:21888
	s_waitcnt lgkmcnt(8)
	v_mfma_f32_16x16x32_bf16 v[94:97], v[200:203], v[228:231], v[94:97]
	ds_read_b128 v[228:231], v165 offset:26240
	s_waitcnt lgkmcnt(8)
	v_mfma_f32_16x16x32_bf16 v[66:69], v[200:203], v[232:235], v[66:69]
	ds_read_b128 v[232:235], v165 offset:30592
	s_waitcnt lgkmcnt(7)
	v_mfma_f32_16x16x32_bf16 v[70:73], v[244:247], v[204:207], v[70:73]
	s_waitcnt lgkmcnt(6)
	v_mfma_f32_16x16x32_bf16 v[74:77], v[244:247], v[208:211], v[74:77]
	s_waitcnt lgkmcnt(5)
	v_mfma_f32_16x16x32_bf16 v[78:81], v[244:247], v[212:215], v[78:81]
	s_waitcnt lgkmcnt(4)
	v_mfma_f32_16x16x32_bf16 v[82:85], v[244:247], v[216:219], v[82:85]
	s_waitcnt lgkmcnt(3)
	v_mfma_f32_16x16x32_bf16 v[188:191], v[244:247], v[220:223], v[86:89]
	s_waitcnt lgkmcnt(2)
	v_mfma_f32_16x16x32_bf16 v[192:195], v[244:247], v[224:227], v[90:93]
	s_waitcnt lgkmcnt(1)
	v_mfma_f32_16x16x32_bf16 v[196:199], v[244:247], v[228:231], v[94:97]
	s_waitcnt lgkmcnt(0)
	v_mfma_f32_16x16x32_bf16 v[66:69], v[244:247], v[232:235], v[66:69]
	ds_read_b128 v[178:181], v160 offset:192
	ds_read_b128 v[86:89], v165 offset:192
	s_waitcnt lgkmcnt(0)
	v_mfma_f32_16x16x32_bf16 v[86:89], v[178:181], v[86:89], v[70:73]
	s_nop 2
	ds_read_b128 v[70:73], v165 offset:4544
	s_waitcnt lgkmcnt(0)
	v_mfma_f32_16x16x32_bf16 v[94:97], v[178:181], v[70:73], v[74:77]
	ds_read_b128 v[70:73], v165 offset:8896
	s_nop 1
	ds_read_b128 v[74:77], v165 offset:21952
	s_waitcnt lgkmcnt(1)
	v_mfma_f32_16x16x32_bf16 v[78:81], v[178:181], v[70:73], v[78:81]
	ds_read_b128 v[70:73], v165 offset:13248
	s_waitcnt lgkmcnt(0)
	v_mfma_f32_16x16x32_bf16 v[90:93], v[178:181], v[70:73], v[82:85]
	ds_read_b128 v[70:73], v165 offset:17600
	v_mfma_f32_16x16x32_bf16 v[82:85], v[178:181], v[74:77], v[192:195]
	ds_read_b128 v[74:77], v165 offset:26304
	s_waitcnt lgkmcnt(1)
	v_mfma_f32_16x16x32_bf16 v[70:73], v[178:181], v[70:73], v[188:191]
	s_nop 2
	ds_read_b128 v[188:191], v165 offset:30656
	s_waitcnt lgkmcnt(1)
	v_mfma_f32_16x16x32_bf16 v[74:77], v[178:181], v[74:77], v[196:199]
	s_waitcnt lgkmcnt(0)
	v_mfma_f32_16x16x32_bf16 v[66:69], v[178:181], v[188:191], v[66:69]
	ds_read2_b32 v[178:179], v161 offset1:16
	v_lshlrev_b32_e32 v180, 16, v42
	v_and_b32_e32 v42, 0xffff0000, v42
	s_waitcnt lgkmcnt(0)
	v_add_f32_e32 v86, v86, v178
	v_add_f32_e32 v87, v87, v178
	v_mul_f32_e32 v86, v86, v180
	v_mul_f32_e32 v42, v87, v42
	v_cvt_pk_bf16_f32 v42, v86, v42
	v_add_f32_e32 v86, v88, v178
	v_lshlrev_b32_e32 v87, 16, v43
	v_mul_f32_e32 v86, v86, v87
	v_add_f32_e32 v87, v89, v178
	v_and_b32_e32 v43, 0xffff0000, v43
	v_mul_f32_e32 v43, v87, v43
	v_cvt_pk_bf16_f32 v43, v86, v43
	v_add_f32_e32 v86, v94, v179
	v_lshlrev_b32_e32 v87, 16, v44
	v_mul_f32_e32 v86, v86, v87
	v_add_f32_e32 v87, v95, v179
	v_and_b32_e32 v44, 0xffff0000, v44
	v_mul_f32_e32 v44, v87, v44
	v_cvt_pk_bf16_f32 v44, v86, v44
	v_add_f32_e32 v86, v96, v179
	v_lshlrev_b32_e32 v87, 16, v45
	v_mul_f32_e32 v86, v86, v87
	v_add_f32_e32 v87, v97, v179
	v_and_b32_e32 v45, 0xffff0000, v45
	v_mul_f32_e32 v45, v87, v45
	v_cvt_pk_bf16_f32 v45, v86, v45
	v_lshl_or_b32 v94, v177, 4, v156
	v_permlane16_swap_b32_e32 v42, v44
	v_permlane16_swap_b32_e32 v43, v45
	v_mad_i64_i32 v[88:89], s[16:17], v94, s85, v[154:155]
	global_store_dwordx4 v[88:89], v[42:45], off
	ds_read2_b32 v[42:43], v161 offset0:32 offset1:48
	s_nop 0
	v_lshlrev_b32_e32 v45, 16, v30
	v_and_b32_e32 v30, 0xffff0000, v30
	s_waitcnt lgkmcnt(0)
	v_add_f32_e32 v44, v78, v42
	v_mul_f32_e32 v44, v44, v45
	v_add_f32_e32 v45, v79, v42
	v_mul_f32_e32 v30, v45, v30
	v_cvt_pk_bf16_f32 v30, v44, v30
	v_add_f32_e32 v44, v80, v42
	v_lshlrev_b32_e32 v45, 16, v31
	v_add_f32_e32 v42, v81, v42
	v_and_b32_e32 v31, 0xffff0000, v31
	v_mul_f32_e32 v44, v44, v45
	v_mul_f32_e32 v31, v42, v31
	v_cvt_pk_bf16_f32 v31, v44, v31
	v_add_f32_e32 v42, v90, v43
	v_lshlrev_b32_e32 v44, 16, v32
	v_mul_f32_e32 v42, v42, v44
	v_add_f32_e32 v44, v91, v43
	v_and_b32_e32 v32, 0xffff0000, v32
	v_mul_f32_e32 v32, v44, v32
	v_cvt_pk_bf16_f32 v32, v42, v32
	v_add_f32_e32 v42, v92, v43
	v_lshlrev_b32_e32 v44, 16, v33
	v_add_f32_e32 v43, v93, v43
	v_and_b32_e32 v33, 0xffff0000, v33
	v_mul_f32_e32 v42, v42, v44
	v_mul_f32_e32 v33, v43, v33
	v_cvt_pk_bf16_f32 v33, v42, v33
	v_or_b32_e32 v42, 32, v94
	v_permlane16_swap_b32_e32 v30, v32
	v_permlane16_swap_b32_e32 v31, v33
	v_mad_i64_i32 v[86:87], s[16:17], v42, s85, v[154:155]
	global_store_dwordx4 v[86:87], v[30:33], off
	ds_read2_b32 v[30:31], v161 offset0:64 offset1:80
	s_nop 0
	v_lshlrev_b32_e32 v33, 16, v22
	v_and_b32_e32 v22, 0xffff0000, v22
	s_waitcnt lgkmcnt(0)
	v_add_f32_e32 v32, v70, v30
	v_mul_f32_e32 v32, v32, v33
	v_add_f32_e32 v33, v71, v30
	v_mul_f32_e32 v22, v33, v22
	v_cvt_pk_bf16_f32 v22, v32, v22
	v_add_f32_e32 v32, v72, v30
	v_lshlrev_b32_e32 v33, 16, v23
	v_add_f32_e32 v30, v73, v30
	v_and_b32_e32 v23, 0xffff0000, v23
	v_mul_f32_e32 v32, v32, v33
	v_mul_f32_e32 v23, v30, v23
	v_cvt_pk_bf16_f32 v23, v32, v23
	v_add_f32_e32 v30, v82, v31
	v_lshlrev_b32_e32 v32, 16, v24
	v_mul_f32_e32 v30, v30, v32
	v_add_f32_e32 v32, v83, v31
	v_and_b32_e32 v24, 0xffff0000, v24
	v_mul_f32_e32 v24, v32, v24
	v_cvt_pk_bf16_f32 v24, v30, v24
	v_add_f32_e32 v30, v84, v31
	v_lshlrev_b32_e32 v32, 16, v25
	v_add_f32_e32 v31, v85, v31
	v_and_b32_e32 v25, 0xffff0000, v25
	v_mul_f32_e32 v30, v30, v32
	v_mul_f32_e32 v25, v31, v25
	v_cvt_pk_bf16_f32 v25, v30, v25
	v_or_b32_e32 v30, 64, v94
	v_permlane16_swap_b32_e32 v22, v24
	v_permlane16_swap_b32_e32 v23, v25
	v_mad_i64_i32 v[82:83], s[16:17], v30, s85, v[154:155]
	global_store_dwordx4 v[82:83], v[22:25], off
	ds_read2_b32 v[22:23], v161 offset0:96 offset1:112
	s_nop 0
	v_lshlrev_b32_e32 v25, 16, v18
	v_and_b32_e32 v18, 0xffff0000, v18
	s_waitcnt lgkmcnt(0)
	v_add_f32_e32 v24, v74, v22
	v_mul_f32_e32 v24, v24, v25
	v_add_f32_e32 v25, v75, v22
	v_mul_f32_e32 v18, v25, v18
	v_cvt_pk_bf16_f32 v18, v24, v18
	v_add_f32_e32 v24, v76, v22
	v_lshlrev_b32_e32 v25, 16, v19
	v_add_f32_e32 v22, v77, v22
	v_and_b32_e32 v19, 0xffff0000, v19
	v_mul_f32_e32 v24, v24, v25
	v_mul_f32_e32 v19, v22, v19
	v_cvt_pk_bf16_f32 v19, v24, v19
	v_add_f32_e32 v22, v66, v23
	v_lshlrev_b32_e32 v24, 16, v20
	v_mul_f32_e32 v22, v22, v24
	v_add_f32_e32 v24, v67, v23
	v_and_b32_e32 v20, 0xffff0000, v20
	v_mul_f32_e32 v20, v24, v20
	v_cvt_pk_bf16_f32 v20, v22, v20
	v_add_f32_e32 v22, v68, v23
	v_lshlrev_b32_e32 v24, 16, v21
	v_add_f32_e32 v23, v69, v23
	v_and_b32_e32 v21, 0xffff0000, v21
	v_mul_f32_e32 v22, v22, v24
	v_mul_f32_e32 v21, v23, v21
	v_cvt_pk_bf16_f32 v21, v22, v21
	v_or_b32_e32 v22, 0x60, v94
	v_permlane16_swap_b32_e32 v18, v20
	v_permlane16_swap_b32_e32 v19, v21
	v_mad_i64_i32 v[84:85], s[16:17], v22, s85, v[154:155]
	global_store_dwordx4 v[84:85], v[18:21], off
	ds_read_b128 v[18:21], v167
	ds_read_b128 v[22:25], v167 offset:16
	ds_read_b128 v[30:33], v167 offset:32
	ds_read_b128 v[42:45], v167 offset:48
	v_lshlrev_b32_e32 v66, 16, v46
	s_waitcnt lgkmcnt(3)
	v_sub_f32_e32 v18, v66, v18
	v_mul_f32_e32 v18, v19, v18
	v_and_b32_e32 v19, 0xffff0000, v46
	v_sub_f32_e32 v19, v19, v20
	v_mul_f32_e32 v19, v21, v19
	v_lshlrev_b32_e32 v20, 16, v47
	v_and_b32_e32 v21, 0xffff0000, v47
	s_waitcnt lgkmcnt(2)
	v_sub_f32_e32 v20, v20, v22
	v_sub_f32_e32 v21, v21, v24
	v_mul_f32_e32 v20, v23, v20
	v_mul_f32_e32 v21, v25, v21
	v_lshlrev_b32_e32 v22, 16, v48
	v_and_b32_e32 v23, 0xffff0000, v48
	v_lshlrev_b32_e32 v24, 16, v49
	v_and_b32_e32 v25, 0xffff0000, v49
	s_waitcnt lgkmcnt(1)
	v_sub_f32_e32 v22, v22, v30
	v_sub_f32_e32 v23, v23, v32
	s_waitcnt lgkmcnt(0)
	v_sub_f32_e32 v24, v24, v42
	v_sub_f32_e32 v25, v25, v44
	v_fma_f32 v18, v176, v18, v175
	v_fma_f32 v19, v176, v19, v175
	v_fma_f32 v20, v176, v20, v175
	v_fma_f32 v21, v176, v21, v175
	v_mul_f32_e32 v22, v31, v22
	v_mul_f32_e32 v23, v33, v23
	v_mul_f32_e32 v24, v43, v24
	v_mul_f32_e32 v25, v45, v25
	v_fma_f32 v22, v176, v22, v175
	v_fma_f32 v23, v176, v23, v175
	v_fma_f32 v24, v176, v24, v175
	v_fmac_f32_e32 v175, v176, v25
	v_cvt_pk_bf16_f32 v18, v18, v19
	v_cvt_pk_bf16_f32 v19, v20, v21
	v_cvt_pk_bf16_f32 v20, v22, v23
	v_cvt_pk_bf16_f32 v21, v24, v175
	ds_write_b128 v168, v[18:21] offset:34816
	ds_read_b128 v[18:21], v167
	ds_read_b128 v[22:25], v167 offset:16
	ds_read_b128 v[30:33], v167 offset:32
	ds_read_b128 v[42:45], v167 offset:48
	v_lshlrev_b32_e32 v46, 16, v38
	s_waitcnt lgkmcnt(3)
	v_sub_f32_e32 v18, v46, v18
	v_mul_f32_e32 v18, v19, v18
	v_and_b32_e32 v19, 0xffff0000, v38
	v_sub_f32_e32 v19, v19, v20
	v_mul_f32_e32 v19, v21, v19
	v_lshlrev_b32_e32 v20, 16, v39
	v_and_b32_e32 v21, 0xffff0000, v39
	s_waitcnt lgkmcnt(2)
	v_sub_f32_e32 v20, v20, v22
	v_sub_f32_e32 v21, v21, v24
	v_mul_f32_e32 v20, v23, v20
	v_mul_f32_e32 v21, v25, v21
	v_lshlrev_b32_e32 v22, 16, v40
	v_and_b32_e32 v23, 0xffff0000, v40
	v_lshlrev_b32_e32 v24, 16, v41
	v_and_b32_e32 v25, 0xffff0000, v41
	s_waitcnt lgkmcnt(1)
	v_sub_f32_e32 v22, v22, v30
	v_sub_f32_e32 v23, v23, v32
	s_waitcnt lgkmcnt(0)
	v_sub_f32_e32 v24, v24, v42
	v_sub_f32_e32 v25, v25, v44
	v_fma_f32 v18, v174, v18, v173
	v_fma_f32 v19, v174, v19, v173
	v_fma_f32 v20, v174, v20, v173
	v_fma_f32 v21, v174, v21, v173
	v_mul_f32_e32 v22, v31, v22
	v_mul_f32_e32 v23, v33, v23
	v_mul_f32_e32 v24, v43, v24
	v_mul_f32_e32 v25, v45, v25
	v_fma_f32 v22, v174, v22, v173
	v_fma_f32 v23, v174, v23, v173
	v_fma_f32 v24, v174, v24, v173
	v_fmac_f32_e32 v173, v174, v25
	v_cvt_pk_bf16_f32 v18, v18, v19
	v_cvt_pk_bf16_f32 v19, v20, v21
	v_cvt_pk_bf16_f32 v20, v22, v23
	v_cvt_pk_bf16_f32 v21, v24, v173
	ds_write_b128 v168, v[18:21] offset:43520
	ds_read_b128 v[18:21], v167
	ds_read_b128 v[22:25], v167 offset:16
	ds_read_b128 v[30:33], v167 offset:32
	ds_read_b128 v[38:41], v167 offset:48
	v_lshlrev_b32_e32 v42, 16, v34
	s_waitcnt lgkmcnt(3)
	v_sub_f32_e32 v18, v42, v18
	v_mul_f32_e32 v18, v19, v18
	v_and_b32_e32 v19, 0xffff0000, v34
	v_sub_f32_e32 v19, v19, v20
	v_mul_f32_e32 v19, v21, v19
	v_lshlrev_b32_e32 v20, 16, v35
	v_and_b32_e32 v21, 0xffff0000, v35
	s_waitcnt lgkmcnt(2)
	v_sub_f32_e32 v20, v20, v22
	v_sub_f32_e32 v21, v21, v24
	v_mul_f32_e32 v20, v23, v20
	v_mul_f32_e32 v21, v25, v21
	v_lshlrev_b32_e32 v22, 16, v36
	v_and_b32_e32 v23, 0xffff0000, v36
	v_lshlrev_b32_e32 v24, 16, v37
	v_and_b32_e32 v25, 0xffff0000, v37
	s_waitcnt lgkmcnt(1)
	v_sub_f32_e32 v22, v22, v30
	v_sub_f32_e32 v23, v23, v32
	s_waitcnt lgkmcnt(0)
	v_sub_f32_e32 v24, v24, v38
	v_sub_f32_e32 v25, v25, v40
	v_fma_f32 v18, v172, v18, v171
	v_fma_f32 v19, v172, v19, v171
	v_fma_f32 v20, v172, v20, v171
	v_fma_f32 v21, v172, v21, v171
	v_mul_f32_e32 v22, v31, v22
	v_mul_f32_e32 v23, v33, v23
	v_mul_f32_e32 v24, v39, v24
	v_mul_f32_e32 v25, v41, v25
	v_fma_f32 v22, v172, v22, v171
	v_fma_f32 v23, v172, v23, v171
	v_fma_f32 v24, v172, v24, v171
	v_fmac_f32_e32 v171, v172, v25
	v_cvt_pk_bf16_f32 v18, v18, v19
	v_cvt_pk_bf16_f32 v19, v20, v21
	v_cvt_pk_bf16_f32 v20, v22, v23
	v_cvt_pk_bf16_f32 v21, v24, v171
	ds_write_b128 v168, v[18:21] offset:52224
	ds_read_b128 v[18:21], v167
	ds_read_b128 v[22:25], v167 offset:16
	ds_read_b128 v[30:33], v167 offset:32
	ds_read_b128 v[34:37], v167 offset:48
	v_lshlrev_b32_e32 v38, 16, v26
	s_waitcnt lgkmcnt(3)
	v_sub_f32_e32 v18, v38, v18
	v_mul_f32_e32 v18, v19, v18
	v_and_b32_e32 v19, 0xffff0000, v26
	v_sub_f32_e32 v19, v19, v20
	v_mul_f32_e32 v19, v21, v19
	v_lshlrev_b32_e32 v20, 16, v27
	v_and_b32_e32 v21, 0xffff0000, v27
	s_waitcnt lgkmcnt(2)
	v_sub_f32_e32 v20, v20, v22
	v_sub_f32_e32 v21, v21, v24
	v_mul_f32_e32 v20, v23, v20
	v_mul_f32_e32 v21, v25, v21
	v_lshlrev_b32_e32 v22, 16, v28
	v_and_b32_e32 v23, 0xffff0000, v28
	v_lshlrev_b32_e32 v24, 16, v29
	v_and_b32_e32 v25, 0xffff0000, v29
	v_fma_f32 v18, v170, v18, v169
	s_waitcnt lgkmcnt(1)
	v_sub_f32_e32 v22, v22, v30
	v_sub_f32_e32 v23, v23, v32
	s_waitcnt lgkmcnt(0)
	v_sub_f32_e32 v24, v24, v34
	v_sub_f32_e32 v25, v25, v36
	v_fma_f32 v19, v170, v19, v169
	v_fma_f32 v20, v170, v20, v169
	v_fma_f32 v21, v170, v21, v169
	v_mul_f32_e32 v22, v31, v22
	v_mul_f32_e32 v23, v33, v23
	v_mul_f32_e32 v24, v35, v24
	v_mul_f32_e32 v25, v37, v25
	v_cvt_pk_bf16_f32 v18, v18, v19
	v_fma_f32 v22, v170, v22, v169
	v_fma_f32 v23, v170, v23, v169
	v_fma_f32 v24, v170, v24, v169
	v_fmac_f32_e32 v169, v170, v25
	v_cvt_pk_bf16_f32 v19, v20, v21
	v_cvt_pk_bf16_f32 v20, v22, v23
	v_cvt_pk_bf16_f32 v21, v24, v169
	ds_write_b128 v168, v[18:21] offset:60928
	v_add_co_u32_e32 v18, vcc, s15, v140
	s_mov_b32 s15, 0xa00000
	s_nop 0
	v_addc_co_u32_e32 v19, vcc, 0, v141, vcc
	s_waitcnt lgkmcnt(0)
	s_barrier
	global_load_dwordx4 v[46:49], v[18:19], off
	global_load_dword v96, v[142:143], off offset:1024
	global_load_dword v97, v[144:145], off offset:1024
	v_add_co_u32_e32 v18, vcc, s15, v140
	s_mov_b32 s15, 0xc00000
	s_nop 0
	v_addc_co_u32_e32 v19, vcc, 0, v141, vcc
	global_load_dwordx4 v[38:41], v[18:19], off
	global_load_dword v94, v[142:143], off offset:1152
	global_load_dword v95, v[144:145], off offset:1152
	v_add_co_u32_e32 v18, vcc, s15, v140
	s_mov_b32 s15, 0xe00000
	s_nop 0
	v_addc_co_u32_e32 v19, vcc, 0, v141, vcc
	global_load_dwordx4 v[34:37], v[18:19], off
	global_load_dword v92, v[142:143], off offset:1280
	global_load_dword v93, v[144:145], off offset:1280
	v_add_co_u32_e32 v18, vcc, s15, v140
	s_nop 1
	v_addc_co_u32_e32 v19, vcc, 0, v141, vcc
	global_load_dwordx4 v[26:29], v[18:19], off
	global_load_dword v90, v[142:143], off offset:1408
	global_load_dword v91, v[144:145], off offset:1408
	global_load_dwordx4 v[78:81], v[146:147], off offset:512
	global_load_dwordx4 v[74:77], v[148:149], off offset:512
	global_load_dwordx4 v[70:73], v[150:151], off offset:512
	global_load_dwordx4 v[66:69], v[152:153], off offset:512
	ds_read_b128 v[18:21], v160 offset:34816
	ds_read_b128 v[22:25], v165
	ds_read_b128 v[30:33], v165 offset:4352
	ds_read_b128 v[42:45], v165 offset:8704
	ds_read_b128 v[140:143], v165 offset:13056
	ds_read_b128 v[144:147], v165 offset:17408
	ds_read_b128 v[148:151], v165 offset:21760
	ds_read_b128 v[152:155], v165 offset:26112
	ds_read_b128 v[170:173], v165 offset:30464
	ds_read_b128 v[200:203], v160 offset:34880
	s_waitcnt lgkmcnt(8)
	v_mfma_f32_16x16x32_bf16 v[22:25], v[18:21], v[22:25], 0
	ds_read_b128 v[204:207], v165 offset:64
	s_and_b64 vcc, exec, s[12:13]
	s_waitcnt lgkmcnt(8)
	v_mfma_f32_16x16x32_bf16 v[30:33], v[18:21], v[30:33], 0
	ds_read_b128 v[208:211], v165 offset:4416
	s_waitcnt lgkmcnt(8)
	v_mfma_f32_16x16x32_bf16 v[42:45], v[18:21], v[42:45], 0
	ds_read_b128 v[212:215], v165 offset:8768
	s_waitcnt lgkmcnt(8)
	v_mfma_f32_16x16x32_bf16 v[140:143], v[18:21], v[140:143], 0
	ds_read_b128 v[216:219], v165 offset:13120
	s_waitcnt lgkmcnt(8)
	v_mfma_f32_16x16x32_bf16 v[144:147], v[18:21], v[144:147], 0
	ds_read_b128 v[220:223], v165 offset:17472
	s_waitcnt lgkmcnt(8)
	v_mfma_f32_16x16x32_bf16 v[148:151], v[18:21], v[148:151], 0
	ds_read_b128 v[224:227], v165 offset:21824
	s_waitcnt lgkmcnt(8)
	v_mfma_f32_16x16x32_bf16 v[152:155], v[18:21], v[152:155], 0
	ds_read_b128 v[228:231], v165 offset:26176
	s_waitcnt lgkmcnt(8)
	v_mfma_f32_16x16x32_bf16 v[18:21], v[18:21], v[170:173], 0
	ds_read_b128 v[232:235], v165 offset:30528
	ds_read_b128 v[244:247], v160 offset:34944
	s_waitcnt lgkmcnt(8)
	v_mfma_f32_16x16x32_bf16 v[22:25], v[200:203], v[204:207], v[22:25]
	ds_read_b128 v[204:207], v165 offset:128
	s_waitcnt lgkmcnt(8)
	v_mfma_f32_16x16x32_bf16 v[30:33], v[200:203], v[208:211], v[30:33]
	ds_read_b128 v[208:211], v165 offset:4480
	s_waitcnt lgkmcnt(8)
	v_mfma_f32_16x16x32_bf16 v[42:45], v[200:203], v[212:215], v[42:45]
	ds_read_b128 v[212:215], v165 offset:8832
	s_waitcnt lgkmcnt(8)
	v_mfma_f32_16x16x32_bf16 v[140:143], v[200:203], v[216:219], v[140:143]
	ds_read_b128 v[216:219], v165 offset:13184
	s_waitcnt lgkmcnt(8)
	v_mfma_f32_16x16x32_bf16 v[144:147], v[200:203], v[220:223], v[144:147]
	ds_read_b128 v[220:223], v165 offset:17536
	s_waitcnt lgkmcnt(8)
	v_mfma_f32_16x16x32_bf16 v[148:151], v[200:203], v[224:227], v[148:151]
	ds_read_b128 v[224:227], v165 offset:21888
	s_waitcnt lgkmcnt(8)
	v_mfma_f32_16x16x32_bf16 v[152:155], v[200:203], v[228:231], v[152:155]
	ds_read_b128 v[228:231], v165 offset:26240
	s_waitcnt lgkmcnt(8)
	v_mfma_f32_16x16x32_bf16 v[18:21], v[200:203], v[232:235], v[18:21]
	ds_read_b128 v[232:235], v165 offset:30592
	s_waitcnt lgkmcnt(7)
	v_mfma_f32_16x16x32_bf16 v[174:177], v[244:247], v[204:207], v[22:25]
	s_waitcnt lgkmcnt(6)
	v_mfma_f32_16x16x32_bf16 v[30:33], v[244:247], v[208:211], v[30:33]
	s_waitcnt lgkmcnt(5)
	v_mfma_f32_16x16x32_bf16 v[42:45], v[244:247], v[212:215], v[42:45]
	s_waitcnt lgkmcnt(4)
	v_mfma_f32_16x16x32_bf16 v[140:143], v[244:247], v[216:219], v[140:143]
	s_waitcnt lgkmcnt(3)
	v_mfma_f32_16x16x32_bf16 v[144:147], v[244:247], v[220:223], v[144:147]
	s_waitcnt lgkmcnt(2)
	v_mfma_f32_16x16x32_bf16 v[148:151], v[244:247], v[224:227], v[148:151]
	s_waitcnt lgkmcnt(1)
	v_mfma_f32_16x16x32_bf16 v[152:155], v[244:247], v[228:231], v[152:155]
	s_waitcnt lgkmcnt(0)
	v_mfma_f32_16x16x32_bf16 v[22:25], v[244:247], v[232:235], v[18:21]
	ds_read_b128 v[170:173], v160 offset:35008
	s_nop 1
	ds_read_b128 v[18:21], v165 offset:192
	s_waitcnt lgkmcnt(0)
	v_mfma_f32_16x16x32_bf16 v[174:177], v[170:173], v[18:21], v[174:177]
	ds_read_b128 v[18:21], v165 offset:4544
	s_waitcnt lgkmcnt(0)
	v_mfma_f32_16x16x32_bf16 v[178:181], v[170:173], v[18:21], v[30:33]
	ds_read_b128 v[18:21], v165 offset:8896
	s_waitcnt lgkmcnt(0)
	v_mfma_f32_16x16x32_bf16 v[188:191], v[170:173], v[18:21], v[42:45]
	ds_read_b128 v[18:21], v165 offset:13248
	s_waitcnt lgkmcnt(0)
	v_mfma_f32_16x16x32_bf16 v[140:143], v[170:173], v[18:21], v[140:143]
	ds_read_b128 v[18:21], v165 offset:17600
	s_waitcnt lgkmcnt(0)
	v_mfma_f32_16x16x32_bf16 v[30:33], v[170:173], v[18:21], v[144:147]
	ds_read_b128 v[18:21], v165 offset:21952
	s_nop 1
	ds_read_b128 v[144:147], v165 offset:30656
	s_waitcnt lgkmcnt(0)
	v_mfma_f32_16x16x32_bf16 v[22:25], v[170:173], v[144:147], v[22:25]
	ds_read2_b32 v[144:145], v161 offset1:16
	v_lshlrev_b32_e32 v147, 16, v62
	v_and_b32_e32 v62, 0xffff0000, v62
	v_mfma_f32_16x16x32_bf16 v[42:45], v[170:173], v[18:21], v[148:151]
	ds_read_b128 v[18:21], v165 offset:26304
	s_waitcnt lgkmcnt(1)
	v_add_f32_e32 v146, v174, v144
	v_mul_f32_e32 v146, v146, v147
	v_add_f32_e32 v147, v175, v144
	v_mul_f32_e32 v62, v147, v62
	v_cvt_pk_bf16_f32 v62, v146, v62
	v_add_f32_e32 v146, v176, v144
	v_lshlrev_b32_e32 v147, 16, v63
	v_add_f32_e32 v144, v177, v144
	v_and_b32_e32 v63, 0xffff0000, v63
	v_mul_f32_e32 v146, v146, v147
	v_mul_f32_e32 v63, v144, v63
	v_cvt_pk_bf16_f32 v63, v146, v63
	v_add_f32_e32 v144, v178, v145
	v_lshlrev_b32_e32 v146, 16, v64
	v_mul_f32_e32 v144, v144, v146
	v_add_f32_e32 v146, v179, v145
	v_and_b32_e32 v64, 0xffff0000, v64
	v_mul_f32_e32 v64, v146, v64
	v_cvt_pk_bf16_f32 v64, v144, v64
	v_add_f32_e32 v144, v180, v145
	v_lshlrev_b32_e32 v146, 16, v65
	v_add_f32_e32 v145, v181, v145
	v_and_b32_e32 v65, 0xffff0000, v65
	v_mul_f32_e32 v65, v145, v65
	v_mul_f32_e32 v144, v144, v146
	v_cvt_pk_bf16_f32 v65, v144, v65
	v_permlane16_swap_b32_e32 v62, v64
	v_permlane16_swap_b32_e32 v63, v65
	global_store_dwordx4 v[88:89], v[62:65], off offset:256
	ds_read2_b32 v[62:63], v161 offset0:32 offset1:48
	s_waitcnt lgkmcnt(1)
	v_mfma_f32_16x16x32_bf16 v[18:21], v[170:173], v[18:21], v[152:155]
	v_lshlrev_b32_e32 v65, 16, v58
	v_and_b32_e32 v58, 0xffff0000, v58
	s_waitcnt lgkmcnt(0)
	v_add_f32_e32 v64, v188, v62
	v_mul_f32_e32 v64, v64, v65
	v_add_f32_e32 v65, v189, v62
	v_mul_f32_e32 v58, v65, v58
	v_cvt_pk_bf16_f32 v58, v64, v58
	v_add_f32_e32 v64, v190, v62
	v_lshlrev_b32_e32 v65, 16, v59
	v_add_f32_e32 v62, v191, v62
	v_and_b32_e32 v59, 0xffff0000, v59
	v_mul_f32_e32 v64, v64, v65
	v_mul_f32_e32 v59, v62, v59
	v_cvt_pk_bf16_f32 v59, v64, v59
	v_add_f32_e32 v62, v140, v63
	v_lshlrev_b32_e32 v64, 16, v60
	v_mul_f32_e32 v62, v62, v64
	v_add_f32_e32 v64, v141, v63
	v_and_b32_e32 v60, 0xffff0000, v60
	v_mul_f32_e32 v60, v64, v60
	v_cvt_pk_bf16_f32 v60, v62, v60
	v_add_f32_e32 v62, v142, v63
	v_lshlrev_b32_e32 v64, 16, v61
	v_add_f32_e32 v63, v143, v63
	v_and_b32_e32 v61, 0xffff0000, v61
	v_mul_f32_e32 v61, v63, v61
	v_mul_f32_e32 v62, v62, v64
	v_cvt_pk_bf16_f32 v61, v62, v61
	v_permlane16_swap_b32_e32 v58, v60
	v_permlane16_swap_b32_e32 v59, v61
	global_store_dwordx4 v[86:87], v[58:61], off offset:256
	ds_read2_b32 v[58:59], v161 offset0:64 offset1:80
	s_waitcnt lgkmcnt(0)
	v_add_f32_e32 v30, v30, v58
	v_lshlrev_b32_e32 v60, 16, v54
	v_add_f32_e32 v31, v31, v58
	v_and_b32_e32 v54, 0xffff0000, v54
	v_mul_f32_e32 v30, v30, v60
	v_mul_f32_e32 v31, v31, v54
	v_cvt_pk_bf16_f32 v30, v30, v31
	v_add_f32_e32 v31, v32, v58
	v_lshlrev_b32_e32 v32, 16, v55
	v_mul_f32_e32 v31, v31, v32
	v_add_f32_e32 v32, v33, v58
	v_and_b32_e32 v33, 0xffff0000, v55
	v_mul_f32_e32 v32, v32, v33
	v_cvt_pk_bf16_f32 v31, v31, v32
	v_add_f32_e32 v32, v42, v59
	v_lshlrev_b32_e32 v33, 16, v56
	v_mul_f32_e32 v32, v32, v33
	v_add_f32_e32 v33, v43, v59
	v_and_b32_e32 v42, 0xffff0000, v56
	v_mul_f32_e32 v33, v33, v42
	v_cvt_pk_bf16_f32 v32, v32, v33
	v_add_f32_e32 v33, v44, v59
	v_lshlrev_b32_e32 v42, 16, v57
	v_mul_f32_e32 v33, v33, v42
	v_add_f32_e32 v42, v45, v59
	v_and_b32_e32 v43, 0xffff0000, v57
	v_mul_f32_e32 v42, v42, v43
	v_cvt_pk_bf16_f32 v33, v33, v42
	v_permlane16_swap_b32_e32 v30, v32
	v_permlane16_swap_b32_e32 v31, v33
	global_store_dwordx4 v[82:83], v[30:33], off offset:256
	ds_read2_b32 v[30:31], v161 offset0:96 offset1:112
	s_waitcnt lgkmcnt(0)
	v_add_f32_e32 v18, v18, v30
	s_waitcnt vmcnt(23)
	v_mov_b32_e32 v32, v52
	s_nop 1
	v_permlane16_swap_b32_e32 v50, v32
	v_lshlrev_b32_e32 v42, 16, v50
	v_mov_b32_e32 v33, v53
	v_mul_f32_e32 v18, v18, v42
	v_add_f32_e32 v19, v19, v30
	v_and_b32_e32 v42, 0xffff0000, v50
	v_permlane16_swap_b32_e32 v51, v33
	v_mul_f32_e32 v19, v19, v42
	v_cvt_pk_bf16_f32 v18, v18, v19
	v_add_f32_e32 v19, v20, v30
	v_lshlrev_b32_e32 v20, 16, v51
	v_mul_f32_e32 v19, v19, v20
	v_add_f32_e32 v20, v21, v30
	v_and_b32_e32 v21, 0xffff0000, v51
	v_mul_f32_e32 v20, v20, v21
	v_cvt_pk_bf16_f32 v19, v19, v20
	v_add_f32_e32 v20, v22, v31
	v_lshlrev_b32_e32 v21, 16, v32
	v_mul_f32_e32 v20, v20, v21
	v_add_f32_e32 v21, v23, v31
	v_and_b32_e32 v22, 0xffff0000, v32
	v_mul_f32_e32 v21, v21, v22
	v_cvt_pk_bf16_f32 v20, v20, v21
	v_add_f32_e32 v21, v24, v31
	v_lshlrev_b32_e32 v22, 16, v33
	v_mul_f32_e32 v21, v21, v22
	v_add_f32_e32 v22, v25, v31
	v_and_b32_e32 v23, 0xffff0000, v33
	v_mul_f32_e32 v22, v22, v23
	v_cvt_pk_bf16_f32 v21, v21, v22
	v_permlane16_swap_b32_e32 v18, v20
	v_permlane16_swap_b32_e32 v19, v21
	global_store_dwordx4 v[84:85], v[18:21], off offset:256
	ds_read_b128 v[18:21], v167
	ds_read_b128 v[22:25], v167 offset:16
	ds_read_b128 v[30:33], v167 offset:32
	ds_read_b128 v[42:45], v167 offset:48
	s_waitcnt vmcnt(19)
	v_lshlrev_b32_e32 v50, 16, v46
	s_waitcnt lgkmcnt(3)
	v_sub_f32_e32 v18, v50, v18
	v_mul_f32_e32 v18, v19, v18
	v_and_b32_e32 v19, 0xffff0000, v46
	v_sub_f32_e32 v19, v19, v20
	v_mul_f32_e32 v19, v21, v19
	v_lshlrev_b32_e32 v20, 16, v47
	v_and_b32_e32 v21, 0xffff0000, v47
	s_waitcnt lgkmcnt(2)
	v_sub_f32_e32 v20, v20, v22
	v_sub_f32_e32 v21, v21, v24
	v_mul_f32_e32 v20, v23, v20
	v_mul_f32_e32 v21, v25, v21
	v_lshlrev_b32_e32 v22, 16, v48
	v_and_b32_e32 v23, 0xffff0000, v48
	v_lshlrev_b32_e32 v24, 16, v49
	v_and_b32_e32 v25, 0xffff0000, v49
	s_waitcnt lgkmcnt(1)
	v_sub_f32_e32 v22, v22, v30
	v_sub_f32_e32 v23, v23, v32
	s_waitcnt lgkmcnt(0)
	v_sub_f32_e32 v24, v24, v42
	v_sub_f32_e32 v25, v25, v44
	s_waitcnt vmcnt(17)
	v_fma_f32 v18, v96, v18, v97
	v_fma_f32 v19, v96, v19, v97
	v_fma_f32 v20, v96, v20, v97
	v_fma_f32 v21, v96, v21, v97
	v_mul_f32_e32 v22, v31, v22
	v_mul_f32_e32 v23, v33, v23
	v_mul_f32_e32 v24, v43, v24
	v_mul_f32_e32 v25, v45, v25
	v_fma_f32 v22, v96, v22, v97
	v_fma_f32 v23, v96, v23, v97
	v_fma_f32 v24, v96, v24, v97
	v_fma_f32 v25, v96, v25, v97
	v_cvt_pk_bf16_f32 v18, v18, v19
	v_cvt_pk_bf16_f32 v19, v20, v21
	v_cvt_pk_bf16_f32 v20, v22, v23
	v_cvt_pk_bf16_f32 v21, v24, v25
	ds_write_b128 v168, v[18:21]
	ds_read_b128 v[18:21], v167
	ds_read_b128 v[22:25], v167 offset:16
	ds_read_b128 v[30:33], v167 offset:32
	ds_read_b128 v[42:45], v167 offset:48
	s_waitcnt vmcnt(16)
	v_lshlrev_b32_e32 v50, 16, v38
	s_waitcnt lgkmcnt(3)
	v_sub_f32_e32 v18, v50, v18
	v_mul_f32_e32 v18, v19, v18
	v_and_b32_e32 v19, 0xffff0000, v38
	v_sub_f32_e32 v19, v19, v20
	v_mul_f32_e32 v19, v21, v19
	v_lshlrev_b32_e32 v20, 16, v39
	v_and_b32_e32 v21, 0xffff0000, v39
	s_waitcnt lgkmcnt(2)
	v_sub_f32_e32 v20, v20, v22
	v_sub_f32_e32 v21, v21, v24
	v_mul_f32_e32 v20, v23, v20
	v_mul_f32_e32 v21, v25, v21
	v_lshlrev_b32_e32 v22, 16, v40
	v_and_b32_e32 v23, 0xffff0000, v40
	v_lshlrev_b32_e32 v24, 16, v41
	v_and_b32_e32 v25, 0xffff0000, v41
	s_waitcnt lgkmcnt(1)
	v_sub_f32_e32 v22, v22, v30
	v_sub_f32_e32 v23, v23, v32
	s_waitcnt lgkmcnt(0)
	v_sub_f32_e32 v24, v24, v42
	v_sub_f32_e32 v25, v25, v44
	s_waitcnt vmcnt(14)
	v_fma_f32 v18, v94, v18, v95
	v_fma_f32 v19, v94, v19, v95
	v_fma_f32 v20, v94, v20, v95
	v_fma_f32 v21, v94, v21, v95
	v_mul_f32_e32 v22, v31, v22
	v_mul_f32_e32 v23, v33, v23
	v_mul_f32_e32 v24, v43, v24
	v_mul_f32_e32 v25, v45, v25
	v_fma_f32 v22, v94, v22, v95
	v_fma_f32 v23, v94, v23, v95
	v_fma_f32 v24, v94, v24, v95
	v_fma_f32 v25, v94, v25, v95
	v_cvt_pk_bf16_f32 v18, v18, v19
	v_cvt_pk_bf16_f32 v19, v20, v21
	v_cvt_pk_bf16_f32 v20, v22, v23
	v_cvt_pk_bf16_f32 v21, v24, v25
	ds_write_b128 v168, v[18:21] offset:8704
	ds_read_b128 v[18:21], v167
	ds_read_b128 v[22:25], v167 offset:16
	ds_read_b128 v[30:33], v167 offset:32
	ds_read_b128 v[42:45], v167 offset:48
	s_waitcnt vmcnt(13)
	v_lshlrev_b32_e32 v50, 16, v34
	s_waitcnt lgkmcnt(3)
	v_sub_f32_e32 v18, v50, v18
	v_mul_f32_e32 v18, v19, v18
	v_and_b32_e32 v19, 0xffff0000, v34
	v_sub_f32_e32 v19, v19, v20
	v_mul_f32_e32 v19, v21, v19
	v_lshlrev_b32_e32 v20, 16, v35
	v_and_b32_e32 v21, 0xffff0000, v35
	s_waitcnt lgkmcnt(2)
	v_sub_f32_e32 v20, v20, v22
	v_sub_f32_e32 v21, v21, v24
	v_mul_f32_e32 v20, v23, v20
	v_mul_f32_e32 v21, v25, v21
	v_lshlrev_b32_e32 v22, 16, v36
	v_and_b32_e32 v23, 0xffff0000, v36
	v_lshlrev_b32_e32 v24, 16, v37
	v_and_b32_e32 v25, 0xffff0000, v37
	s_waitcnt lgkmcnt(1)
	v_sub_f32_e32 v22, v22, v30
	v_sub_f32_e32 v23, v23, v32
	s_waitcnt lgkmcnt(0)
	v_sub_f32_e32 v24, v24, v42
	v_sub_f32_e32 v25, v25, v44
	s_waitcnt vmcnt(11)
	v_fma_f32 v18, v92, v18, v93
	v_fma_f32 v19, v92, v19, v93
	v_fma_f32 v20, v92, v20, v93
	v_fma_f32 v21, v92, v21, v93
	v_mul_f32_e32 v22, v31, v22
	v_mul_f32_e32 v23, v33, v23
	v_mul_f32_e32 v24, v43, v24
	v_mul_f32_e32 v25, v45, v25
	v_fma_f32 v22, v92, v22, v93
	v_fma_f32 v23, v92, v23, v93
	v_fma_f32 v24, v92, v24, v93
	v_fma_f32 v25, v92, v25, v93
	v_cvt_pk_bf16_f32 v18, v18, v19
	v_cvt_pk_bf16_f32 v19, v20, v21
	v_cvt_pk_bf16_f32 v20, v22, v23
	v_cvt_pk_bf16_f32 v21, v24, v25
	ds_write_b128 v168, v[18:21] offset:17408
	ds_read_b128 v[18:21], v167
	ds_read_b128 v[22:25], v167 offset:16
	ds_read_b128 v[30:33], v167 offset:32
	ds_read_b128 v[42:45], v167 offset:48
	s_waitcnt vmcnt(10)
	v_lshlrev_b32_e32 v50, 16, v26
	s_waitcnt lgkmcnt(3)
	v_sub_f32_e32 v18, v50, v18
	v_mul_f32_e32 v18, v19, v18
	v_and_b32_e32 v19, 0xffff0000, v26
	v_sub_f32_e32 v19, v19, v20
	v_mul_f32_e32 v19, v21, v19
	v_lshlrev_b32_e32 v20, 16, v27
	v_and_b32_e32 v21, 0xffff0000, v27
	s_waitcnt lgkmcnt(2)
	v_sub_f32_e32 v20, v20, v22
	v_sub_f32_e32 v21, v21, v24
	v_mul_f32_e32 v20, v23, v20
	v_mul_f32_e32 v21, v25, v21
	v_lshlrev_b32_e32 v22, 16, v28
	v_and_b32_e32 v23, 0xffff0000, v28
	v_lshlrev_b32_e32 v24, 16, v29
	v_and_b32_e32 v25, 0xffff0000, v29
	s_waitcnt lgkmcnt(1)
	v_sub_f32_e32 v22, v22, v30
	v_sub_f32_e32 v23, v23, v32
	s_waitcnt lgkmcnt(0)
	v_sub_f32_e32 v24, v24, v42
	v_sub_f32_e32 v25, v25, v44
	s_waitcnt vmcnt(8)
	v_fma_f32 v18, v90, v18, v91
	v_fma_f32 v19, v90, v19, v91
	v_fma_f32 v20, v90, v20, v91
	v_fma_f32 v21, v90, v21, v91
	v_mul_f32_e32 v22, v31, v22
	v_mul_f32_e32 v23, v33, v23
	v_mul_f32_e32 v24, v43, v24
	v_mul_f32_e32 v25, v45, v25
	v_fma_f32 v22, v90, v22, v91
	v_fma_f32 v23, v90, v23, v91
	v_fma_f32 v24, v90, v24, v91
	v_fma_f32 v25, v90, v25, v91
	v_cvt_pk_bf16_f32 v18, v18, v19
	v_cvt_pk_bf16_f32 v19, v20, v21
	v_cvt_pk_bf16_f32 v20, v22, v23
	v_cvt_pk_bf16_f32 v21, v24, v25
	ds_write_b128 v168, v[18:21] offset:26112
	s_waitcnt lgkmcnt(0)
	s_barrier
	s_cbranch_vccnz .LBB0_922
	s_lshl_b32 s16, s14, 4
	s_and_b32 s15, s14, 7
	s_cmp_lg_u32 s15, 0
	s_cbranch_scc0 .LBB0_923
	s_lshl_b32 s17, s15, 7
	s_and_saveexec_b64 s[18:19], s[4:5]
	s_cbranch_execz .LBB0_911
	s_branch .LBB0_924
